# stage-1 differential-attention items assigned statically per XCD (all 32 query blocks of a batch-head on one XCD, n and 31-n paired per workgroup) for groups 1-3; redundant pre-fetch barrier dropped
# speedup vs baseline: 1.0168x; 1.0106x over previous
.Lnc5_okf:
.Lnc5_done:
.LBB0_842:
	s_or_b64 exec, exec, s[0:1]
	v_readlane_b32 s26, v240, 27
	s_lshl_b32 s0, s26, 1
	v_readlane_b32 s1, v241, 30
	s_add_i32 s84, s0, s1
	s_lshl_b64 s[38:39], s[84:85], 2
	v_readlane_b32 s0, v243, 47
	s_add_u32 s24, s0, s38
	v_readlane_b32 s0, v243, 48
	s_addc_u32 s25, s0, s39
	s_cmp_eq_u32 s26, 0
	s_cselect_b64 s[78:79], -1, 0
	s_and_b64 s[0:1], s[78:79], exec
	s_cselect_b32 s64, 0x80, 0
	s_cselect_b32 s96, 2, 0
	s_cselect_b32 s97, 0, 0x200
	s_cmp_eq_u32 s94, 0x100
	s_cselect_b32 s96, s96, 2
	s_cselect_b32 s97, s97, 0
	s_or_b32 s65, s64, 0xa00
	s_barrier
	v_readlane_b32 s27, v240, 28
	s_branch .LBB0_845

.LBB0_845:
	s_cmp_ge_u32 s96, 2
	s_cbranch_scc1 .Lsq_dyn
	v_readlane_b32 s76, v241, 19
	s_nop 3
	s_and_b32 s0, s76, 7
	s_lshr_b32 s76, s76, 3
	s_lshl_b32 s0, s0, 5
	s_cmp_eq_u32 s96, 0
	s_cbranch_scc1 .Lsq_j0
	s_sub_u32 s76, 31, s76
	s_add_u32 s0, s0, 0x100
.Lsq_j0:
	s_add_u32 s76, s76, s0
	s_add_u32 s96, s96, 1
	s_mov_b64 s[0:1], -1
	s_branch .Lsq_go
.Lsq_dyn:
	s_waitcnt vmcnt(2)
	v_mov_b32_e32 v0, v166
	s_nop 0
	v_cmp_eq_u32_e32 vcc, 0, v0
	s_and_saveexec_b64 s[0:1], vcc
	s_cbranch_execz .LBB0_849
	s_mov_b64 s[28:29], exec
	v_mbcnt_lo_u32_b32 v0, s28, 0
	v_mbcnt_hi_u32_b32 v0, s29, v0
	v_cmp_eq_u32_e32 vcc, 0, v0
	s_and_saveexec_b64 s[26:27], vcc
	s_cbranch_execz .LBB0_848
	s_bcnt1_i32_b64 s28, s[28:29]
	v_mov_b32_e32 v1, s28
	global_atomic_add v1, v65, v1, s[24:25] sc0

.LBB0_849:
	s_or_b64 exec, exec, s[0:1]
	s_waitcnt lgkmcnt(0)
	s_barrier
	ds_read_b32 v0, v173
	s_mov_b64 s[0:1], -1
	s_waitcnt lgkmcnt(0)
	v_add_u32_e32 v0, s97, v0
	v_cmp_le_i32_e32 vcc, s65, v0
	v_readfirstlane_b32 s76, v0
	s_cbranch_vccnz .LBB0_844
.Lsq_go:
	s_cmp_ge_i32 s76, s64
	s_cbranch_scc0 .LBB0_921
	s_sub_i32 s77, s76, s64
	s_cmpk_gt_i32 s77, 0x1ff
	s_cbranch_scc0 .LBB0_906
	s_cmpk_gt_u32 s77, 0x7ff
	s_cbranch_scc0 .LBB0_895
	s_add_i32 s28, s77, 0xfffff800
	s_and_b32 s0, s28, 31
	s_bfe_u32 s1, s28, 0x20005
	s_lshr_b32 s26, s28, 7
	s_lshl_b32 s26, s26, 12
	s_lshl_b32 s0, s0, 7
	s_add_i32 s26, s26, s0
	s_mul_hi_u32 s27, s26, 0x4600
	s_mul_i32 s0, s26, 0x4600
	s_lshl_b32 s29, s1, 7
	s_add_u32 s44, s92, s0
	s_addc_u32 s45, s93, s27
	s_add_u32 s44, s44, 0x23604900
	s_addc_u32 s45, s45, 0
	s_add_u32 s44, s44, s29
	s_addc_u32 s45, s45, 0
	s_add_u32 s44, s44, 0x2000
	s_addc_u32 s45, s45, 0
	v_lshrrev_b32_e32 v0, 3, v166
	v_and_b32_e32 v1, 7, v166
	v_mul_u32_u24_e32 v2, 0x4600, v0
	v_lshl_add_u32 v2, v1, 4, v2
	v_add_u32_e32 v3, 0x118000, v2
	global_load_dwordx4 v[4:7], v2, s[44:45]
	global_load_dwordx4 v[8:11], v2, s[44:45] offset:512
	global_load_dwordx4 v[12:15], v3, s[44:45]
	global_load_dwordx4 v[16:19], v3, s[44:45] offset:512
	v_readlane_b32 s30, v241, 20
	v_readlane_b32 s31, v241, 21
	v_mov_b32_e32 v20, 0
	v_mov_b32_e32 v21, 0
	v_mov_b32_e32 v22, 0
	v_mov_b32_e32 v23, 0
	v_mov_b32_e32 v24, 0
	v_mov_b32_e32 v25, 0
	v_mov_b32_e32 v26, 0
	v_mov_b32_e32 v27, 0
	s_nop 0
	s_and_b64 vcc, exec, s[30:31]
	s_cbranch_vccz .Lh1_nolb
	v_readlane_b32 s58, v245, 14
	v_readlane_b32 s59, v245, 15
	s_lshl_b32 s29, s1, 8
	v_lshl_add_u32 v36, v1, 5, s29
	s_nop 3
	global_load_dwordx4 v[40:43], v36, s[58:59]
	global_load_dwordx4 v[44:47], v36, s[58:59] offset:16
	global_load_dwordx4 v[48:51], v36, s[58:59] offset:1024
	global_load_dwordx4 v[52:55], v36, s[58:59] offset:1040
	s_waitcnt vmcnt(0)
	v_sub_f32_e32 v56, v40, v48
	v_mul_f32_e32 v56, 0x3fb8aa3b, v56
	v_exp_f32_e32 v56, v56
	s_nop 0
	v_add_f32_e32 v56, 1.0, v56
	v_div_scale_f32 v57, s[36:37], v56, v56, 1.0
	v_rcp_f32_e32 v58, v57
	v_div_scale_f32 v59, vcc, 1.0, v56, 1.0
	v_fma_f32 v60, -v57, v58, 1.0
	v_fmac_f32_e32 v58, v60, v58
	v_mul_f32_e32 v60, v59, v58
	v_fma_f32 v61, -v57, v60, v59
	v_fmac_f32_e32 v60, v61, v58
	v_fma_f32 v57, -v57, v60, v59
	v_div_fmas_f32 v57, v57, v58, v60
	v_div_fixup_f32 v20, v57, v56, 1.0
	v_sub_f32_e32 v56, v41, v49
	v_mul_f32_e32 v56, 0x3fb8aa3b, v56
	v_exp_f32_e32 v56, v56
	s_nop 0
	v_add_f32_e32 v56, 1.0, v56
	v_div_scale_f32 v57, s[36:37], v56, v56, 1.0
	v_rcp_f32_e32 v58, v57
	v_div_scale_f32 v59, vcc, 1.0, v56, 1.0
	v_fma_f32 v60, -v57, v58, 1.0
	v_fmac_f32_e32 v58, v60, v58
	v_mul_f32_e32 v60, v59, v58
	v_fma_f32 v61, -v57, v60, v59
	v_fmac_f32_e32 v60, v61, v58
	v_fma_f32 v57, -v57, v60, v59
	v_div_fmas_f32 v57, v57, v58, v60
	v_div_fixup_f32 v21, v57, v56, 1.0
	v_sub_f32_e32 v56, v42, v50
	v_mul_f32_e32 v56, 0x3fb8aa3b, v56
	v_exp_f32_e32 v56, v56
	s_nop 0
	v_add_f32_e32 v56, 1.0, v56
	v_div_scale_f32 v57, s[36:37], v56, v56, 1.0
	v_rcp_f32_e32 v58, v57
	v_div_scale_f32 v59, vcc, 1.0, v56, 1.0
	v_fma_f32 v60, -v57, v58, 1.0
	v_fmac_f32_e32 v58, v60, v58
	v_mul_f32_e32 v60, v59, v58
	v_fma_f32 v61, -v57, v60, v59
	v_fmac_f32_e32 v60, v61, v58
	v_fma_f32 v57, -v57, v60, v59
	v_div_fmas_f32 v57, v57, v58, v60
	v_div_fixup_f32 v22, v57, v56, 1.0
	v_sub_f32_e32 v56, v43, v51
	v_mul_f32_e32 v56, 0x3fb8aa3b, v56
	v_exp_f32_e32 v56, v56
	s_nop 0
	v_add_f32_e32 v56, 1.0, v56
	v_div_scale_f32 v57, s[36:37], v56, v56, 1.0
	v_rcp_f32_e32 v58, v57
	v_div_scale_f32 v59, vcc, 1.0, v56, 1.0
	v_fma_f32 v60, -v57, v58, 1.0
	v_fmac_f32_e32 v58, v60, v58
	v_mul_f32_e32 v60, v59, v58
	v_fma_f32 v61, -v57, v60, v59
	v_fmac_f32_e32 v60, v61, v58
	v_fma_f32 v57, -v57, v60, v59
	v_div_fmas_f32 v57, v57, v58, v60
	v_div_fixup_f32 v23, v57, v56, 1.0
	v_sub_f32_e32 v56, v44, v52
	v_mul_f32_e32 v56, 0x3fb8aa3b, v56
	v_exp_f32_e32 v56, v56
	s_nop 0
	v_add_f32_e32 v56, 1.0, v56
	v_div_scale_f32 v57, s[36:37], v56, v56, 1.0
	v_rcp_f32_e32 v58, v57
	v_div_scale_f32 v59, vcc, 1.0, v56, 1.0
	v_fma_f32 v60, -v57, v58, 1.0
	v_fmac_f32_e32 v58, v60, v58
	v_mul_f32_e32 v60, v59, v58
	v_fma_f32 v61, -v57, v60, v59
	v_fmac_f32_e32 v60, v61, v58
	v_fma_f32 v57, -v57, v60, v59
	v_div_fmas_f32 v57, v57, v58, v60
	v_div_fixup_f32 v24, v57, v56, 1.0
	v_sub_f32_e32 v56, v45, v53
	v_mul_f32_e32 v56, 0x3fb8aa3b, v56
	v_exp_f32_e32 v56, v56
	s_nop 0
	v_add_f32_e32 v56, 1.0, v56
	v_div_scale_f32 v57, s[36:37], v56, v56, 1.0
	v_rcp_f32_e32 v58, v57
	v_div_scale_f32 v59, vcc, 1.0, v56, 1.0
	v_fma_f32 v60, -v57, v58, 1.0
	v_fmac_f32_e32 v58, v60, v58
	v_mul_f32_e32 v60, v59, v58
	v_fma_f32 v61, -v57, v60, v59
	v_fmac_f32_e32 v60, v61, v58
	v_fma_f32 v57, -v57, v60, v59
	v_div_fmas_f32 v57, v57, v58, v60
	v_div_fixup_f32 v25, v57, v56, 1.0
	v_sub_f32_e32 v56, v46, v54
	v_mul_f32_e32 v56, 0x3fb8aa3b, v56
	v_exp_f32_e32 v56, v56
	s_nop 0
	v_add_f32_e32 v56, 1.0, v56
	v_div_scale_f32 v57, s[36:37], v56, v56, 1.0
	v_rcp_f32_e32 v58, v57
	v_div_scale_f32 v59, vcc, 1.0, v56, 1.0
	v_fma_f32 v60, -v57, v58, 1.0
	v_fmac_f32_e32 v58, v60, v58
	v_mul_f32_e32 v60, v59, v58
	v_fma_f32 v61, -v57, v60, v59
	v_fmac_f32_e32 v60, v61, v58
	v_fma_f32 v57, -v57, v60, v59
	v_div_fmas_f32 v57, v57, v58, v60
	v_div_fixup_f32 v26, v57, v56, 1.0
	v_sub_f32_e32 v56, v47, v55
	v_mul_f32_e32 v56, 0x3fb8aa3b, v56
	v_exp_f32_e32 v56, v56
	s_nop 0
	v_add_f32_e32 v56, 1.0, v56
	v_div_scale_f32 v57, s[36:37], v56, v56, 1.0
	v_rcp_f32_e32 v58, v57
	v_div_scale_f32 v59, vcc, 1.0, v56, 1.0
	v_fma_f32 v60, -v57, v58, 1.0
	v_fmac_f32_e32 v58, v60, v58
	v_mul_f32_e32 v60, v59, v58
	v_fma_f32 v61, -v57, v60, v59
	v_fmac_f32_e32 v60, v61, v58
	v_fma_f32 v57, -v57, v60, v59
	v_div_fmas_f32 v57, v57, v58, v60
	v_div_fixup_f32 v27, v57, v56, 1.0
